# chunk scan: LDS-DMA issued by a loader wave (waves 4), shared 4-buffer ring for both v-halves, scalar y-store base
# speedup vs baseline: 1.0188x; 1.0064x over previous
.LBB0_972:
	s_andn2_b64 vcc, exec, s[0:1]
	s_cbranch_vccnz .LBB0_1156
	v_mov_b32_e32 v150, v234
	v_readlane_b32 s0, v253, 7
	v_readlane_b32 s1, v253, 8
	s_cmp_lt_i32 s62, 2
	s_nop 0
	v_writelane_b32 v253, s1, 8
	v_writelane_b32 v253, s0, 7
	s_mov_b64 s[0:1], -1
	s_cbranch_scc0 .LBB0_995
	s_setprio 3
	s_lshl_b32 s101, s62, 2
	s_add_i32 s101, s101, 0x20804
	v_readlane_b32 s100, v254, 57
	s_mov_b32 s98, 0
	s_mov_b32 s99, 0xb800
	s_add_i32 s100, s100, 1
	s_lshl_b32 s100, s100, 12
	v_readlane_b32 s0, v253, 61
	v_readlane_b32 s1, v253, 7
	v_writelane_b32 v255, s62, 8
	v_mov_b32_e32 v0, s0
	ds_read_b64 v[2:3], v0
	v_readlane_b32 s0, v253, 8
	s_lshl_b32 s0, s1, 1
	s_add_i32 s5, s0, s62
	s_cmpk_gt_i32 s5, 0x8ff
	s_waitcnt lgkmcnt(0)
	v_readfirstlane_b32 s0, v2
	v_readfirstlane_b32 s1, v3
	s_cbranch_scc1 .LBB0_994
	s_add_u32 s2, s0, 0x5c400000
	v_writelane_b32 v255, s2, 13
	s_addc_u32 s2, s1, 0
	v_writelane_b32 v255, s2, 14
	s_add_u32 s2, s0, 0x72e00000
	v_writelane_b32 v255, s2, 6
	s_addc_u32 s2, s1, 0
	s_add_u32 s27, s0, 0x74e00000
	s_addc_u32 s23, s1, 0
	v_writelane_b32 v255, s2, 0
	s_add_u32 s0, s0, 0x25400000
	v_writelane_b32 v255, s0, 15
	s_addc_u32 s0, s1, 0
	v_writelane_b32 v255, s0, 16
	v_readlane_b32 s0, v253, 8
	s_lshl_b32 s8, s0, 1
	v_readlane_b32 s0, v255, 8
	s_mov_b32 s0, 0
	s_add_i32 s22, s0, 0
	v_readlane_b32 s0, v254, 60
	v_readlane_b32 s1, v254, 61
	s_lshl_b32 s0, s0, 1
	s_mov_b32 s1, s17
	v_writelane_b32 v255, s0, 17
	v_ashrrev_i32_e32 v2, 5, v150
	v_lshlrev_b32_e32 v5, 9, v2
	v_writelane_b32 v255, s1, 18
	s_add_i32 s0, s22, 0x2000
	v_writelane_b32 v255, s0, 4
	s_add_i32 s0, s22, 0x3000
	v_writelane_b32 v255, s0, 5
	s_add_i32 s0, s22, 0x4000
	v_writelane_b32 v255, s0, 9
	s_add_i32 s0, s22, 0x5000
	v_writelane_b32 v255, s0, 10
	s_add_i32 s0, s22, 0x5800
	v_writelane_b32 v255, s0, 11
	s_add_i32 s0, s22, 0x6c00
	v_writelane_b32 v255, s0, 19
	s_add_i32 s0, s22, 0x7c00
	v_writelane_b32 v255, s0, 20
	s_add_i32 s0, s22, 0x8c00
	v_writelane_b32 v255, s0, 21
	s_add_i32 s0, s22, 0x9c00
	v_writelane_b32 v255, s0, 22
	s_add_i32 s0, s22, 0x6000
	v_writelane_b32 v255, s0, 23
	s_add_i32 s0, s22, 0x7000
	v_writelane_b32 v255, s0, 24
	s_add_i32 s0, s22, 0x8000
	v_writelane_b32 v255, s0, 25
	s_add_i32 s0, s22, 0x9000
	v_writelane_b32 v255, s0, 26
	s_add_i32 s0, s22, 0xa000
	v_writelane_b32 v255, s0, 27
	s_add_i32 s0, s22, 0x6400
	v_writelane_b32 v255, s0, 28
	s_add_i32 s0, s22, 0x7400
	v_writelane_b32 v255, s0, 29
	s_add_i32 s0, s22, 0x8400
	v_writelane_b32 v255, s0, 30
	s_add_i32 s0, s22, 0x9400
	v_writelane_b32 v255, s0, 31
	s_add_i32 s0, s22, 0xa400
	v_writelane_b32 v255, s0, 32
	s_add_i32 s0, s22, 0x6800
	v_writelane_b32 v255, s0, 33
	s_add_i32 s0, s22, 0x7800
	v_writelane_b32 v255, s0, 34
	s_add_i32 s0, s22, 0x8800
	v_writelane_b32 v255, s0, 35
	s_add_i32 s0, s22, 0x9800
	v_writelane_b32 v255, s0, 36
	s_add_i32 s0, s22, 0xa800
	v_writelane_b32 v255, s0, 37
	s_add_i32 s0, s22, 0xac00
	v_writelane_b32 v255, s0, 38
	s_add_i32 s0, s22, 0xb000
	v_writelane_b32 v255, s0, 39
	s_add_i32 s0, s22, 0xb400
	v_lshlrev_b32_e32 v6, 5, v150
	s_movk_i32 s4, 0x180
	v_writelane_b32 v255, s0, 40
	v_and_or_b32 v5, v6, s4, v5
	s_add_i32 s4, s22, 0x400
	v_writelane_b32 v255, s4, 2
	s_add_i32 s4, s22, 0x1400
	v_writelane_b32 v255, s4, 3
	s_add_i32 s4, s22, 0x2400
	v_writelane_b32 v255, s4, 41
	s_add_i32 s4, s22, 0x3400
	v_writelane_b32 v255, s4, 42
	s_add_i32 s4, s22, 0x4400
	v_writelane_b32 v255, s4, 43
	s_add_i32 s4, s22, 0x800
	v_writelane_b32 v255, s4, 44
	s_add_i32 s4, s22, 0x1800
	v_writelane_b32 v255, s4, 45
	s_add_i32 s4, s22, 0x2800
	v_writelane_b32 v255, s4, 46
	s_add_i32 s4, s22, 0x3800
	v_writelane_b32 v255, s4, 47
	s_add_i32 s4, s22, 0x4800
	v_writelane_b32 v255, s4, 48
	s_add_i32 s4, s22, 0xc00
	v_writelane_b32 v255, s4, 49
	s_add_i32 s4, s22, 0x1c00
	v_writelane_b32 v255, s4, 50
	s_add_i32 s4, s22, 0x2c00
	v_writelane_b32 v255, s4, 51
	s_add_i32 s4, s22, 0x3c00
	v_writelane_b32 v255, s4, 52
	s_add_i32 s4, s22, 0x4c00
	v_and_b32_e32 v0, 31, v150
	s_add_i32 s19, s22, 0x1000
	s_add_i32 s6, s22, 0x5c00
	v_lshlrev_b32_e32 v7, 3, v150
	v_lshlrev_b32_e32 v8, 1, v150
	v_writelane_b32 v255, s4, 53
	s_add_i32 s4, s22, 0x5400
	s_addk_i32 s8, 0xff00
	v_lshlrev_b32_e32 v151, 6, v0
	v_lshlrev_b32_e32 v152, 2, v2
	v_lshlrev_b32_e32 v3, 7, v0
	v_lshlrev_b32_e32 v160, 4, v2
	v_and_b32_e32 v7, 24, v7
	v_and_b32_e32 v8, 32, v8
	v_writelane_b32 v255, s4, 54
	s_cmpk_gt_i32 s5, 0xff
	v_add_u32_e32 v4, v3, v160
	v_or_b32_e32 v161, 1, v152
	v_or_b32_e32 v162, 2, v152
	v_or_b32_e32 v163, 3, v152
	v_add_u32_e32 v164, 8, v152
	v_add_u32_e32 v165, 9, v152
	v_add_u32_e32 v166, 10, v152
	v_add_u32_e32 v167, 11, v152
	v_add_u32_e32 v168, 16, v152
	v_add_u32_e32 v169, 17, v152
	v_add_u32_e32 v170, 18, v152
	v_add_u32_e32 v171, 19, v152
	v_add_u32_e32 v172, 24, v152
	v_add_u32_e32 v173, 25, v152
	v_add_u32_e32 v174, 26, v152
	v_add_u32_e32 v175, 27, v152
	v_or3_b32 v5, v5, v8, v7
	v_add_u32_e32 v3, s22, v3
	v_lshlrev_b32_e32 v2, 3, v2
	v_add_u32_e32 v6, s22, v151
	v_writelane_b32 v255, s6, 55
	s_cselect_b32 s4, s8, 0x900
	v_ashrrev_i32_e32 v153, 31, v152
	v_cmp_lt_i32_e64 s[0:1], v152, v0
	v_cmp_lt_i32_e64 s[2:3], v161, v0
	v_cmp_lt_i32_e64 s[34:35], v162, v0
	v_cmp_lt_i32_e64 s[36:37], v163, v0
	v_cmp_lt_i32_e64 s[38:39], v164, v0
	v_cmp_lt_i32_e64 s[40:41], v165, v0
	v_cmp_lt_i32_e64 s[42:43], v166, v0
	v_cmp_lt_i32_e64 s[44:45], v167, v0
	v_cmp_lt_i32_e64 s[46:47], v168, v0
	v_cmp_lt_i32_e64 s[48:49], v169, v0
	v_cmp_lt_i32_e64 s[50:51], v170, v0
	v_cmp_lt_i32_e64 s[52:53], v171, v0
	v_cmp_lt_i32_e64 s[54:55], v172, v0
	v_cmp_lt_i32_e64 s[56:57], v173, v0
	v_cmp_lt_i32_e64 s[58:59], v174, v0
	v_add_u32_e32 v176, s22, v5
	v_sub_u32_e32 v177, 31, v152
	v_sub_u32_e32 v178, 31, v161
	v_sub_u32_e32 v179, 31, v162
	v_sub_u32_e32 v180, 31, v163
	v_sub_u32_e32 v181, 23, v152
	v_sub_u32_e32 v182, 22, v152
	v_sub_u32_e32 v183, 21, v152
	v_sub_u32_e32 v184, 20, v152
	v_sub_u32_e32 v185, 15, v152
	v_sub_u32_e32 v186, 14, v152
	v_sub_u32_e32 v187, 13, v152
	v_sub_u32_e32 v188, 12, v152
	v_sub_u32_e32 v189, 7, v152
	v_sub_u32_e32 v190, 6, v152
	v_sub_u32_e32 v191, 5, v152
	v_sub_u32_e32 v192, 4, v152
	v_add_u32_e32 v193, s6, v5
	v_writelane_b32 v255, s4, 56
	v_lshlrev_b32_e32 v154, 2, v0
	v_add_u32_e32 v194, s22, v4
	v_add_u32_e32 v195, v3, v2
	v_add_u32_e32 v196, v6, v2
	v_cmp_lt_i32_e64 s[60:61], v175, v0
	v_cmp_gt_i32_e64 s[62:63], v152, v0
	v_cmp_gt_i32_e64 s[64:65], v162, v0
	v_cmp_gt_i32_e64 s[66:67], v163, v0
	v_cmp_gt_i32_e64 s[68:69], v164, v0
	v_cmp_gt_i32_e64 s[70:71], v165, v0
	v_cmp_gt_i32_e64 s[72:73], v166, v0
	v_cmp_gt_i32_e64 s[74:75], v167, v0
	v_cmp_gt_i32_e64 s[76:77], v168, v0
	v_cmp_gt_i32_e64 s[78:79], v169, v0
	v_cmp_gt_i32_e64 s[80:81], v170, v0
	v_cmp_gt_i32_e64 s[82:83], v171, v0
	v_cmp_gt_i32_e64 s[84:85], v172, v0
	v_cmp_gt_i32_e64 s[86:87], v173, v0
	v_cmp_gt_i32_e64 s[88:89], v174, v0
	v_cmp_gt_i32_e64 s[90:91], v175, v0
	s_branch .LBB0_977

.LBB0_982:
	s_and_b64 s[12:13], s[8:9], exec
	s_cselect_b32 s11, 64, 8
	s_lshl_b32 s12, s6, 11
	s_addk_i32 s12, 0x2000
	s_lshl_b32 s13, s6, 8
	s_and_b64 s[8:9], s[8:9], exec
	s_cselect_b32 s12, s12, s13
	s_ashr_i32 s13, s12, 5
	s_add_i32 s14, s11, -1
	s_cmp_eq_u32 s16, 0
	s_cselect_b64 s[92:93], -1, 0
	v_mov_b32_e32 v35, v234
	s_and_b64 s[8:9], s[92:93], exec
	s_mov_b32 s4, s6
	s_cselect_b32 s8, 0, s14
	v_ashrrev_i32_e32 v0, 3, v35
	v_writelane_b32 v255, s4, 62
	v_sub_u32_e32 v34, 31, v0
	s_add_i32 s8, s13, s8
	v_writelane_b32 v255, s5, 63
	v_cndmask_b32_e64 v38, v34, v0, s[92:93]
	s_lshl_b32 s9, s8, 5
	s_lshl_b32 s14, s16, 8
	s_lshl_b32 s16, s16, 9
	v_readlane_b32 s4, v255, 13
	v_add_u32_e32 v38, s9, v38
	s_add_u32 s94, s4, s16
	v_readlane_b32 s4, v255, 14
	v_lshlrev_b32_e32 v42, 4, v35
	v_ashrrev_i32_e32 v39, 31, v38
	s_addc_u32 s95, s4, 0
	v_and_b32_e32 v0, 0x70, v42
	v_lshlrev_b64 v[38:39], 4, v[38:39]
	v_lshl_add_u64 v[36:37], s[94:95], 0, v[0:1]
	v_or_b32_e32 v0, s26, v38
	s_sub_u32 s96, 0, s14
	v_mad_u64_u32 v[40:41], s[14:15], v0, s33, v[36:37]
	v_mad_i32_i24 v41, v39, s33, v41
	s_mov_b32 m0, s22
	s_nop 0
	s_nop 0
	s_mov_b64 s[4:5], 0x80
	v_lshl_add_u64 v[38:39], v[40:41], 0, s[4:5]
	s_mov_b32 m0, s19
	s_nop 0
	s_nop 0
	s_mov_b32 s20, s19
	s_mov_b64 s[18:19], 0x100
	v_lshl_add_u64 v[38:39], v[40:41], 0, s[18:19]
	s_mov_b64 s[24:25], 0x180
	v_readlane_b32 s6, v255, 4
	s_mov_b32 m0, s6
	s_nop 0
	s_nop 0
	v_lshl_add_u64 v[38:39], v[40:41], 0, s[24:25]
	v_readlane_b32 s6, v255, 5
	s_mov_b32 m0, s6
	s_nop 0
	s_nop 0
	v_subrev_co_u32_e32 v38, vcc, s16, v40
	s_mov_b64 s[6:7], 0x400
	s_nop 0
	v_subbrev_co_u32_e32 v39, vcc, 0, v41, vcc
	v_add_u32_e32 v0, 64, v35
	v_lshl_add_u64 v[38:39], v[38:39], 0, s[6:7]
	v_ashrrev_i32_e32 v0, 3, v0
	v_readlane_b32 s15, v255, 9
	s_mov_b32 m0, s15
	s_nop 0
	s_nop 0
	v_sub_u32_e32 v38, 31, v0
	v_cndmask_b32_e64 v0, v38, v0, s[92:93]
	v_add_u32_e32 v38, s9, v0
	v_ashrrev_i32_e32 v39, 31, v38
	v_lshlrev_b64 v[38:39], 4, v[38:39]
	v_or_b32_e32 v0, s26, v38
	v_mad_u64_u32 v[40:41], s[14:15], v0, s33, v[36:37]
	v_mad_i32_i24 v41, v39, s33, v41
	v_readlane_b32 s15, v255, 2
	s_mov_b32 m0, s15
	s_nop 0
	s_nop 0
	v_lshl_add_u64 v[38:39], v[40:41], 0, s[4:5]
	v_readlane_b32 s15, v255, 3
	s_mov_b32 m0, s15
	s_nop 0
	s_nop 0
	v_lshl_add_u64 v[38:39], v[40:41], 0, s[18:19]
	v_readlane_b32 s15, v255, 41
	s_mov_b32 m0, s15
	s_nop 0
	s_nop 0
	v_lshl_add_u64 v[38:39], v[40:41], 0, s[24:25]
	v_readlane_b32 s15, v255, 42
	s_mov_b32 m0, s15
	s_nop 0
	s_nop 0
	v_subrev_co_u32_e32 v38, vcc, s16, v40
	v_add_u32_e32 v0, 0x80, v35
	s_nop 0
	v_subbrev_co_u32_e32 v39, vcc, 0, v41, vcc
	v_lshl_add_u64 v[38:39], v[38:39], 0, s[6:7]
	v_ashrrev_i32_e32 v0, 3, v0
	v_readlane_b32 s15, v255, 43
	s_mov_b32 m0, s15
	s_nop 0
	s_nop 0
	v_sub_u32_e32 v38, 31, v0
	v_cndmask_b32_e64 v0, v38, v0, s[92:93]
	v_add_u32_e32 v38, s9, v0
	v_ashrrev_i32_e32 v39, 31, v38
	v_lshlrev_b64 v[38:39], 4, v[38:39]
	v_or_b32_e32 v0, s26, v38
	v_mad_u64_u32 v[40:41], s[14:15], v0, s33, v[36:37]
	v_mad_i32_i24 v41, v39, s33, v41
	v_readlane_b32 s15, v255, 44
	s_mov_b32 m0, s15
	s_nop 0
	s_nop 0
	v_lshl_add_u64 v[38:39], v[40:41], 0, s[4:5]
	v_readlane_b32 s15, v255, 45
	s_mov_b32 m0, s15
	s_nop 0
	s_nop 0
	v_lshl_add_u64 v[38:39], v[40:41], 0, s[18:19]
	v_readlane_b32 s15, v255, 46
	s_mov_b32 m0, s15
	s_nop 0
	s_nop 0
	v_lshl_add_u64 v[38:39], v[40:41], 0, s[24:25]
	v_add_u32_e32 v0, 0xc0, v35
	v_readlane_b32 s15, v255, 47
	s_mov_b32 m0, s15
	s_nop 0
	s_nop 0
	v_subrev_co_u32_e32 v38, vcc, s16, v40
	v_ashrrev_i32_e32 v0, 3, v0
	v_lshlrev_b32_e32 v34, 3, v35
	v_subbrev_co_u32_e32 v39, vcc, 0, v41, vcc
	v_sub_u32_e32 v35, 31, v0
	v_lshl_add_u64 v[38:39], v[38:39], 0, s[6:7]
	v_cndmask_b32_e64 v0, v35, v0, s[92:93]
	v_readlane_b32 s15, v255, 48
	s_mov_b32 m0, s15
	s_nop 0
	s_nop 0
	v_add_u32_e32 v38, s9, v0
	v_ashrrev_i32_e32 v39, 31, v38
	v_lshlrev_b64 v[38:39], 4, v[38:39]
	v_or_b32_e32 v0, s26, v38
	v_mad_u64_u32 v[36:37], s[14:15], v0, s33, v[36:37]
	v_mad_i32_i24 v37, v39, s33, v37
	v_readlane_b32 s14, v255, 49
	s_mov_b32 m0, s14
	s_nop 0
	s_nop 0
	v_lshl_add_u64 v[38:39], v[36:37], 0, s[4:5]
	v_readlane_b32 s4, v255, 50
	s_mov_b32 m0, s4
	s_nop 0
	s_nop 0
	v_lshl_add_u64 v[38:39], v[36:37], 0, s[18:19]
	v_readlane_b32 s4, v255, 51
	s_mov_b32 m0, s4
	s_nop 0
	s_nop 0
	v_lshl_add_u64 v[38:39], v[36:37], 0, s[24:25]
	v_subrev_co_u32_e32 v36, vcc, s16, v36
	v_readlane_b32 s4, v255, 52
	s_mov_b32 m0, s4
	s_nop 0
	s_nop 0
	s_nop 0
	v_subbrev_co_u32_e32 v37, vcc, 0, v37, vcc
	v_lshl_add_u64 v[36:37], v[36:37], 0, s[6:7]
	v_readlane_b32 s4, v255, 53
	s_mov_b32 m0, s4
	s_nop 0
	s_nop 0
	s_subb_u32 s97, 0, 0
	s_ashr_i32 s9, s8, 31
	v_readlane_b32 s24, v255, 59
	s_lshl_b64 s[8:9], s[8:9], 5
	s_lshl_b32 s16, s24, 4
	s_or_b32 s8, s8, s16
	s_or_b32 s8, s8, s26
	s_lshl_b64 s[14:15], s[8:9], 11
	v_readlane_b32 s4, v255, 6
	s_add_u32 s14, s4, s14
	v_readlane_b32 s4, v255, 0
	s_addc_u32 s15, s4, s15
	v_ashrrev_i32_e32 v35, 31, v34
	s_lshl_b64 s[8:9], s[8:9], 8
	v_lshl_add_u64 v[34:35], v[34:35], 1, s[14:15]
	v_readlane_b32 s4, v255, 10
	s_mov_b32 m0, s4
	s_nop 0
	s_nop 0
	s_add_u32 s8, s27, s8
	v_lshl_add_u64 v[34:35], v[34:35], 0, s[6:7]
	v_readlane_b32 s4, v255, 54
	s_mov_b32 m0, s4
	s_nop 0
	s_nop 0
	s_addc_u32 s9, s23, s9
	v_and_b32_e32 v0, 0xf0, v42
	v_lshl_add_u64 v[34:35], s[8:9], 0, v[0:1]
	v_readlane_b32 s4, v255, 11
	s_mov_b32 m0, s4
	s_nop 0
	s_nop 0
	s_lshl_b32 s14, s10, 6
	s_lshl_b32 s8, s24, 26
	v_readlane_b32 s4, v255, 15
	s_add_u32 s8, s4, s8
	v_readlane_b32 s4, v255, 16
	s_addc_u32 s9, s4, 0
	s_lshl_b32 s15, s26, 8
	s_add_u32 s8, s8, s15
	s_addc_u32 s9, s9, 0
	s_lshl_b32 s10, s10, 7
	s_add_u32 s8, s8, s10
	s_addc_u32 s9, s9, 0
	v_mov_b32_e32 v155, v1
	s_mov_b32 s21, 0
	s_mov_b32 s19, s20
	v_add_u32_e32 v157, s14, v176
	v_lshl_add_u64 v[158:159], s[8:9], 0, v[154:155]
	v_cndmask_b32_e64 v155, v177, v152, s[92:93]
	v_cndmask_b32_e64 v197, v178, v161, s[92:93]
	v_cndmask_b32_e64 v198, v179, v162, s[92:93]
	v_cndmask_b32_e64 v199, v180, v163, s[92:93]
	v_cndmask_b32_e64 v200, v181, v164, s[92:93]
	v_cndmask_b32_e64 v201, v182, v165, s[92:93]
	v_cndmask_b32_e64 v202, v183, v166, s[92:93]
	v_cndmask_b32_e64 v203, v184, v167, s[92:93]
	v_cndmask_b32_e64 v204, v185, v168, s[92:93]
	v_cndmask_b32_e64 v205, v186, v169, s[92:93]
	v_cndmask_b32_e64 v206, v187, v170, s[92:93]
	v_cndmask_b32_e64 v207, v188, v171, s[92:93]
	v_cndmask_b32_e64 v208, v189, v172, s[92:93]
	v_cndmask_b32_e64 v209, v190, v173, s[92:93]
	v_cndmask_b32_e64 v210, v191, v174, s[92:93]
	v_cndmask_b32_e64 v211, v192, v175, s[92:93]
	v_lshl_add_u32 v155, v155, 12, v154
	v_lshl_add_u32 v197, v197, 12, v154
	v_lshl_add_u32 v198, v198, 12, v154
	v_lshl_add_u32 v199, v199, 12, v154
	v_lshl_add_u32 v200, v200, 12, v154
	v_lshl_add_u32 v201, v201, 12, v154
	v_lshl_add_u32 v202, v202, 12, v154
	v_lshl_add_u32 v203, v203, 12, v154
	v_lshl_add_u32 v204, v204, 12, v154
	v_lshl_add_u32 v205, v205, 12, v154
	v_lshl_add_u32 v206, v206, 12, v154
	v_lshl_add_u32 v207, v207, 12, v154
	v_lshl_add_u32 v208, v208, 12, v154
	v_lshl_add_u32 v209, v209, 12, v154
	v_lshl_add_u32 v210, v210, 12, v154
	v_lshl_add_u32 v211, v211, 12, v154
	v_add_u32_e32 v212, s14, v193
	s_or_b32 s16, s26, s16
	s_add_i32 s20, s11, -3
	v_readlane_b32 s25, v255, 60
	s_waitcnt vmcnt(0)
	s_branch .LBB0_984
.LBB0_983:
	ds_read_b128 v[112:115], v194 offset:31744
	ds_read_b128 v[66:69], v194 offset:23552
	ds_read_b128 v[70:73], v194 offset:23584
	ds_read_b128 v[116:119], v194 offset:31776
	s_nop 5
	v_pk_add_f32 v[32:33], v[64:65], v[32:33]
	v_pk_add_f32 v[142:143], v[62:63], v[30:31]
	s_waitcnt lgkmcnt(2)
	v_mfma_f32_32x32x16_bf16 v[76:91], v[112:115], v[66:69], 0
	v_add_f32_e64 v218, v60, v28
	v_add_f32_e64 v219, v61, v29
	v_add_f32_e64 v20, v52, v20
	v_add_f32_e64 v21, v53, v21
	v_add_f32_e64 v18, v50, v18
	v_add_f32_e64 v19, v51, v19
	v_pk_add_f32 v[26:27], v[58:59], v[26:27]
	v_pk_add_f32 v[24:25], v[56:57], v[24:25]
	v_pk_add_f32 v[22:23], v[54:55], v[22:23]
	v_pk_add_f32 v[16:17], v[48:49], v[16:17]
	s_waitcnt lgkmcnt(0)
	v_mfma_f32_32x32x16_bf16 v[76:91], v[116:119], v[70:73], v[76:91]
	ds_read_b128 v[134:137], v194 offset:31808
	ds_read_b128 v[66:69], v194 offset:23616
	ds_read_b128 v[138:141], v194 offset:31840
	ds_read_b128 v[70:73], v194 offset:23648
	v_add_f32_e64 v14, v46, v14
	v_add_f32_e64 v15, v47, v15
	v_pk_add_f32 v[12:13], v[44:45], v[12:13]
	v_pk_add_f32 v[10:11], v[42:43], v[10:11]
	v_pk_add_f32 v[8:9], v[40:41], v[8:9]
	v_pk_add_f32 v[6:7], v[38:39], v[6:7]
	v_pk_add_f32 v[4:5], v[36:37], v[4:5]
	s_waitcnt lgkmcnt(2)
	v_mfma_f32_32x32x16_bf16 v[76:91], v[134:137], v[66:69], v[76:91]
	ds_read_b128 v[66:69], v194 offset:27648
	ds_read_b128 v[146:149], v194 offset:35840
	ds_read_b128 v[28:31], v194 offset:27680
	ds_read_b128 v[214:217], v194 offset:35872
	ds_read_b128 v[50:53], v194 offset:27712
	ds_read_b128 v[56:59], v194 offset:35904
	v_pk_add_f32 v[2:3], v[34:35], v[2:3]
	v_pk_mul_f32 v[22:23], v[126:127], v[22:23]
	s_waitcnt lgkmcnt(6)
	v_mfma_f32_32x32x16_bf16 v[76:91], v[138:141], v[70:73], v[76:91]
	v_mul_f32_e64 v24, v128, v24
	v_mul_f32_e64 v25, v129, v25
	v_mul_f32_e64 v26, v122, v26
	v_mul_f32_e64 v27, v123, v27
	ds_read_b128 v[120:123], v194 offset:27744
	ds_read_b128 v[126:129], v194 offset:35936
	v_pk_mul_f32 v[18:19], v[130:131], v[18:19]
	v_pk_mul_f32 v[20:21], v[132:133], v[20:21]
	v_pk_mul_f32 v[32:33], v[110:111], v[32:33]
	v_pk_mul_f32 v[6:7], v[96:97], v[6:7]
	s_waitcnt lgkmcnt(6)
	v_mfma_f32_32x32x16_bf16 v[60:75], v[66:69], v[146:149], 0
	v_cndmask_b32_e64 v0, 0, v76, s[0:1]
	v_cndmask_b32_e64 v34, 0, v77, s[2:3]
	v_cndmask_b32_e64 v35, 0, v78, s[34:35]
	v_cndmask_b32_e64 v36, 0, v79, s[36:37]
	v_cndmask_b32_e64 v37, 0, v80, s[38:39]
	v_cndmask_b32_e64 v38, 0, v81, s[40:41]
	v_cndmask_b32_e64 v39, 0, v82, s[42:43]
	s_waitcnt lgkmcnt(4)
	v_mfma_f32_32x32x16_bf16 v[60:75], v[28:31], v[214:217], v[60:75]
	v_cndmask_b32_e64 v76, 0, v83, s[44:45]
	v_cvt_pk_bf16_f32 v34, v0, v34
	v_cvt_pk_bf16_f32 v35, v35, v36
	v_cvt_pk_bf16_f32 v36, v37, v38
	v_cvt_pk_bf16_f32 v37, v39, v76
	v_cndmask_b32_e64 v77, 0, v84, s[46:47]
	v_cndmask_b32_e64 v78, 0, v85, s[48:49]
	s_waitcnt lgkmcnt(2)
	v_mfma_f32_32x32x16_bf16 v[60:75], v[50:53], v[56:59], v[60:75]
	v_mul_f32_e64 v28, v124, v218
	v_mul_f32_e64 v29, v125, v219
	v_mul_f32_e64 v30, v108, v142
	v_mul_f32_e64 v31, v109, v143
	v_mul_f32_e64 v8, v98, v8
	v_mul_f32_e64 v9, v99, v9
	v_pk_mul_f32 v[14:15], v[92:93], v[14:15]
	v_cndmask_b32_e64 v92, 0, v90, s[58:59]
	v_cndmask_b32_e64 v93, 0, v91, s[60:61]
	v_cvt_pk_bf16_f32 v96, v77, v78
	v_mfma_f32_32x32x16_bf16 v[40:55], v[112:115], v[146:149], 0
	v_cvt_pk_bf16_f32 v99, v92, v93
	v_mul_f32_e64 v2, v100, v2
	v_mul_f32_e64 v3, v101, v3
	v_add_u32_e32 v100, 0x5800, v195
	v_cvt_pk_bf16_f32 v146, v18, v19
	v_cvt_pk_bf16_f32 v147, v20, v21
	v_cvt_pk_bf16_f32 v148, v22, v23
	v_cvt_pk_bf16_f32 v149, v24, v25
	v_mfma_f32_32x32x16_bf16 v[40:55], v[116:119], v[214:217], v[40:55]
	v_cvt_pk_bf16_f32 v214, v26, v27
	v_cvt_pk_bf16_f32 v215, v28, v29
	v_cvt_pk_bf16_f32 v216, v30, v31
	v_cvt_pk_bf16_f32 v217, v32, v33
	v_mul_f32_e64 v16, v94, v16
	v_mul_f32_e64 v17, v95, v17
	v_pk_mul_f32 v[4:5], v[102:103], v[4:5]
	v_cvt_pk_bf16_f32 v228, v2, v3
	v_mfma_f32_32x32x16_bf16 v[40:55], v[134:137], v[56:59], v[40:55]
	v_cndmask_b32_e64 v56, 0, v86, s[50:51]
	v_cndmask_b32_e64 v57, 0, v87, s[52:53]
	v_cndmask_b32_e64 v58, 0, v88, s[54:55]
	v_cndmask_b32_e64 v59, 0, v89, s[56:57]
	v_cvt_pk_bf16_f32 v97, v56, v57
	v_cvt_pk_bf16_f32 v98, v58, v59
	v_cvt_pk_bf16_f32 v229, v4, v5
	s_waitcnt lgkmcnt(0)
	v_mfma_f32_32x32x16_bf16 v[60:75], v[120:123], v[126:129], v[60:75]
	v_cvt_pk_bf16_f32 v230, v6, v7
	v_cvt_pk_bf16_f32 v231, v8, v9
	v_mul_f32_e64 v10, v104, v10
	v_mul_f32_e64 v11, v105, v11
	v_mul_f32_e64 v12, v106, v12
	v_mul_f32_e64 v13, v107, v13
	v_cvt_pk_bf16_f32 v242, v10, v11
	v_cvt_pk_bf16_f32 v243, v12, v13
	v_cvt_pk_bf16_f32 v244, v14, v15
	v_mfma_f32_32x32x16_bf16 v[40:55], v[138:141], v[126:129], v[40:55]
	ds_read_b64_tr_b16 v[136:137], v212 offset:0x4000
	ds_read_b64_tr_b16 v[138:139], v212 offset:0x4000+1024
	ds_read_b64_tr_b16 v[128:129], v212 offset:0x4000+2048
	ds_read_b64_tr_b16 v[130:131], v212 offset:0x4000+3072
	ds_read_b64_tr_b16 v[120:121], v193 offset:0x1000
	ds_read_b64_tr_b16 v[122:123], v193 offset:0x1000+1024
	ds_read_b64_tr_b16 v[116:117], v193 offset:0x1000+2048
	ds_read_b64_tr_b16 v[118:119], v193 offset:0x1000+3072
	ds_read_b64_tr_b16 v[112:113], v193 offset:0x1000+64
	ds_read_b64_tr_b16 v[114:115], v193 offset:0x1000+64+1024
	ds_read_b64_tr_b16 v[108:109], v193 offset:0x1000+64+2048
	ds_read_b64_tr_b16 v[110:111], v193 offset:0x1000+64+3072
	ds_read_b64_tr_b16 v[140:141], v193 offset:0x2000
	ds_read_b64_tr_b16 v[142:143], v193 offset:0x2000+1024
	ds_read_b64_tr_b16 v[132:133], v193 offset:0x2000+2048
	ds_read_b64_tr_b16 v[134:135], v193 offset:0x2000+3072
	ds_read_b64_tr_b16 v[56:57], v193 offset:0x2000+64
	ds_read_b64_tr_b16 v[58:59], v193 offset:0x2000+64+1024
	ds_read_b64_tr_b16 v[124:125], v193 offset:0x2000+64+2048
	ds_read_b64_tr_b16 v[126:127], v193 offset:0x2000+64+3072
	s_waitcnt lgkmcnt(0)
	v_cvt_pk_bf16_f32 v245, v16, v17
	s_nop 0
	v_cndmask_b32_e64 v60, v60, 0, s[62:63]
	v_cndmask_b32_e64 v61, 0, v61, s[0:1]
	v_cvt_pk_bf16_f32 v60, v60, v61
	v_cndmask_b32_e64 v72, v72, 0, s[84:85]
	s_xor_b32 s14, s21, 0x7fffffe
	v_mfma_f32_32x32x16_bf16 v[76:91], v[34:37], v[136:139], 0
	ds_read2_b64 v[34:37], v100 offset0:128 offset1:130
	s_nop 2
	v_cndmask_b32_e64 v0, v40, 0, s[62:63]
	v_cndmask_b32_e64 v92, 0, v41, s[0:1]
	ds_read2_b64 v[38:41], v100 offset0:132 offset1:134
	v_cndmask_b32_e64 v213, v50, 0, s[80:81]
	v_add_u32_e32 v50, 0xa800, v196
	v_cndmask_b32_e64 v42, v42, 0, s[64:65]
	v_mfma_f32_32x32x16_bf16 v[76:91], v[96:99], v[128:131], v[76:91]
	ds_read2_b64 v[96:99], v100 offset0:140 offset1:142
	v_cndmask_b32_e64 v43, v43, 0, s[66:67]
	v_cndmask_b32_e64 v44, v44, 0, s[68:69]
	v_cndmask_b32_e64 v45, v45, 0, s[70:71]
	v_cndmask_b32_e64 v218, v51, 0, s[82:83]
	v_cndmask_b32_e64 v219, v52, 0, s[84:85]
	v_cndmask_b32_e64 v237, v53, 0, s[86:87]
	s_waitcnt lgkmcnt(2)
	v_mfma_f32_32x32x16_bf16 v[76:91], v[34:37], v[146:149], v[76:91]
	v_cvt_pk_bf16_f32 v34, v0, v92
	ds_read2_b64 v[92:95], v100 offset0:136 offset1:138
	v_cndmask_b32_e64 v37, v46, 0, s[72:73]
	v_cndmask_b32_e64 v46, v47, 0, s[74:75]
	v_cvt_pk_bf16_f32 v35, v42, v43
	v_cvt_pk_bf16_f32 v36, v44, v45
	v_cvt_pk_bf16_f32 v37, v37, v46
	s_waitcnt lgkmcnt(2)
	v_mfma_f32_32x32x16_bf16 v[76:91], v[38:41], v[214:217], v[76:91]
	v_cndmask_b32_e64 v0, v48, 0, s[76:77]
	v_cndmask_b32_e64 v145, v49, 0, s[78:79]
	v_cndmask_b32_e64 v54, v54, 0, s[88:89]
	v_cndmask_b32_e64 v55, v55, 0, s[90:91]
	s_add_i32 s21, s14, s11
	s_and_b64 s[14:15], s[92:93], exec
	s_cselect_b32 s10, s10, s21
	s_waitcnt lgkmcnt(0)
	v_mfma_f32_32x32x16_bf16 v[76:91], v[92:95], v[228:231], v[76:91]
	ds_read2_b64 v[92:95], v50 offset0:128 offset1:130
	ds_read2_b64 v[50:53], v50 offset0:132 offset1:134
	s_lshl_b32 s10, s10, 5
	s_add_i32 s10, s10, s12
	s_add_i32 s20, s20, -2
	s_and_b64 vcc, exec, s[8:9]
	s_mov_b32 s21, s18
	v_mfma_f32_32x32x16_bf16 v[76:91], v[96:99], v[242:245], v[76:91]
	v_mfma_f32_32x32x16_bf16 v[34:49], v[34:37], v[136:139], 0
	s_nop 10
	v_cvt_pk_bf16_f32 v76, v76, v77
	v_cvt_pk_bf16_f32 v77, v78, v79
	v_cvt_pk_bf16_f32 v78, v80, v81
	v_cvt_pk_bf16_f32 v79, v82, v83
	v_cvt_pk_bf16_f32 v80, v88, v89
	v_cvt_pk_bf16_f32 v81, v90, v91
	s_waitcnt lgkmcnt(1)
	v_mfma_f32_32x32x16_bf16 v[92:107], v[92:95], v[76:79], 0
	v_cvt_pk_bf16_f32 v78, v84, v85
	v_cvt_pk_bf16_f32 v79, v86, v87
	v_cvt_pk_bf16_f32 v76, v0, v145
	v_cvt_pk_bf16_f32 v77, v213, v218
	v_add_u32_e32 v0, 0x8800, v195
	s_waitcnt lgkmcnt(0)
	v_mfma_f32_32x32x16_bf16 v[92:107], v[50:53], v[78:81], v[92:107]
	v_cvt_pk_bf16_f32 v78, v219, v237
	v_cvt_pk_bf16_f32 v79, v54, v55
	ds_read2_b64 v[50:53], v0 offset0:128 offset1:130
	s_nop 0
	v_mfma_f32_32x32x16_bf16 v[34:49], v[76:79], v[128:131], v[34:49]
	ds_read2_b64 v[76:79], v0 offset0:132 offset1:134
	s_nop 5
	v_cvt_pk_bf16_f32 v86, v92, v93
	v_cvt_pk_bf16_f32 v87, v94, v95
	v_cvt_pk_bf16_f32 v88, v96, v97
	v_cvt_pk_bf16_f32 v89, v98, v99
	v_cvt_pk_bf16_f32 v82, v100, v101
	v_cvt_pk_bf16_f32 v83, v102, v103
	s_waitcnt lgkmcnt(1)
	v_mfma_f32_32x32x16_bf16 v[34:49], v[50:53], v[146:149], v[34:49]
	ds_read2_b64 v[52:55], v0 offset0:136 offset1:138
	v_cndmask_b32_e64 v50, v68, 0, s[76:77]
	v_cndmask_b32_e64 v51, v69, 0, s[78:79]
	v_cvt_pk_bf16_f32 v50, v50, v51
	v_cndmask_b32_e64 v51, v70, 0, s[80:81]
	v_cndmask_b32_e64 v68, v71, 0, s[82:83]
	v_cvt_pk_bf16_f32 v51, v51, v68
	s_waitcnt lgkmcnt(1)
	v_mfma_f32_32x32x16_bf16 v[34:49], v[76:79], v[214:217], v[34:49]
	ds_read2_b64 v[68:71], v0 offset0:140 offset1:142
	v_cndmask_b32_e64 v0, v62, 0, s[64:65]
	v_cvt_pk_bf16_f32 v84, v104, v105
	v_cvt_pk_bf16_f32 v85, v106, v107
	s_waitcnt lgkmcnt(1)
	v_mfma_f32_32x32x16_bf16 v[34:49], v[52:55], v[228:231], v[34:49]
	v_cndmask_b32_e64 v52, v63, 0, s[66:67]
	v_cndmask_b32_e64 v53, v64, 0, s[68:69]
	v_cndmask_b32_e64 v54, v65, 0, s[70:71]
	v_cndmask_b32_e64 v55, v66, 0, s[72:73]
	v_cndmask_b32_e64 v63, v67, 0, s[74:75]
	v_cvt_pk_bf16_f32 v61, v0, v52
	v_cvt_pk_bf16_f32 v62, v53, v54
	s_waitcnt lgkmcnt(0)
	v_mfma_f32_32x32x16_bf16 v[34:49], v[68:71], v[242:245], v[34:49]
	v_cvt_pk_bf16_f32 v63, v55, v63
	v_cndmask_b32_e64 v0, v73, 0, s[86:87]
	v_cvt_pk_bf16_f32 v52, v72, v0
	v_cndmask_b32_e64 v0, v74, 0, s[88:89]
	v_cndmask_b32_e64 v53, v75, 0, s[90:91]
	v_cvt_pk_bf16_f32 v53, v0, v53
	v_mfma_f32_32x32x16_bf16 v[34:49], v[60:63], v[86:89], v[34:49]
	v_mfma_f32_32x32x16_bf16 v[34:49], v[50:53], v[82:85], v[34:49]
	v_mfma_f32_32x32x16_bf16 v[66:81], v[140:143], v[136:139], 0
	s_movk_i32 s4, 0x1000
	v_mov_b32_e32 v252, s10
	v_mad_u64_u32 v[250:251], s[6:7], v252, s4, v[158:159]
	s_nop 0
	v_readfirstlane_b32 s6, v250
	v_readfirstlane_b32 s7, v251
	s_nop 6
	global_store_dword v155, v34, s[6:7]
	global_store_dword v197, v35, s[6:7]
	global_store_dword v198, v36, s[6:7]
	global_store_dword v199, v37, s[6:7]
	global_store_dword v200, v38, s[6:7]
	global_store_dword v201, v39, s[6:7]
	global_store_dword v202, v40, s[6:7]
	global_store_dword v203, v41, s[6:7]
	global_store_dword v204, v42, s[6:7]
	global_store_dword v205, v43, s[6:7]
	global_store_dword v206, v44, s[6:7]
	global_store_dword v207, v45, s[6:7]
	global_store_dword v208, v46, s[6:7]
	v_mfma_f32_32x32x16_bf16 v[18:33], v[120:123], v[86:89], v[18:33]
	global_store_dword v209, v47, s[6:7]
	v_mfma_f32_32x32x16_bf16 v[50:65], v[56:59], v[136:139], 0
	global_store_dword v210, v48, s[6:7]
	global_store_dword v211, v49, s[6:7]
	ds_read_b128 v[34:37], v144 offset:46080
	ds_read_b128 v[38:41], v144 offset:46112
	ds_read_b128 v[42:45], v144 offset:46144
	ds_read_b128 v[46:49], v144 offset:46176
	v_mfma_f32_32x32x16_bf16 v[2:17], v[112:115], v[86:89], v[2:17]
	v_mfma_f32_32x32x16_bf16 v[66:81], v[132:135], v[128:131], v[66:81]
	v_mfma_f32_32x32x16_bf16 v[18:33], v[116:119], v[82:85], v[18:33]
	v_mfma_f32_32x32x16_bf16 v[50:65], v[124:127], v[128:131], v[50:65]
	s_nop 10
	v_add_f32_e64 v32, v80, v32
	v_add_f32_e64 v33, v81, v33
	v_add_f32_e64 v30, v78, v30
	v_add_f32_e64 v31, v79, v31
	v_add_f32_e64 v28, v76, v28
	v_add_f32_e64 v29, v77, v29
	v_pk_add_f32 v[26:27], v[74:75], v[26:27]
	v_pk_add_f32 v[24:25], v[72:73], v[24:25]
	v_pk_add_f32 v[22:23], v[70:71], v[22:23]
	v_pk_add_f32 v[20:21], v[68:69], v[20:21]
	v_mfma_f32_32x32x16_bf16 v[2:17], v[108:111], v[82:85], v[2:17]
	v_add_f32_e64 v18, v66, v18
	v_add_f32_e64 v19, v67, v19
	s_waitcnt lgkmcnt(3)
	v_mul_f32_e64 v20, v36, v20
	v_mul_f32_e64 v21, v37, v21
	v_pk_mul_f32 v[18:19], v[34:35], v[18:19]
	s_waitcnt lgkmcnt(2)
	v_pk_mul_f32 v[22:23], v[38:39], v[22:23]
	v_pk_mul_f32 v[24:25], v[40:41], v[24:25]
	s_waitcnt lgkmcnt(1)
	v_pk_mul_f32 v[26:27], v[42:43], v[26:27]
	v_pk_mul_f32 v[28:29], v[44:45], v[28:29]
	s_waitcnt lgkmcnt(0)
	v_pk_mul_f32 v[30:31], v[46:47], v[30:31]
	v_pk_mul_f32 v[32:33], v[48:49], v[32:33]
	ds_read_b128 v[34:37], v144 offset:46208
	ds_read_b128 v[38:41], v144 offset:46240
	ds_read_b128 v[42:45], v144 offset:46272
	ds_read_b128 v[46:49], v144 offset:46304
	v_pk_add_f32 v[16:17], v[64:65], v[16:17]
	v_pk_add_f32 v[14:15], v[62:63], v[14:15]
	v_pk_add_f32 v[12:13], v[60:61], v[12:13]
	v_pk_add_f32 v[10:11], v[58:59], v[10:11]
	v_pk_add_f32 v[8:9], v[56:57], v[8:9]
	v_pk_add_f32 v[6:7], v[54:55], v[6:7]
	v_pk_add_f32 v[4:5], v[52:53], v[4:5]
	v_pk_add_f32 v[2:3], v[50:51], v[2:3]
	s_waitcnt lgkmcnt(3)
	v_pk_mul_f32 v[4:5], v[36:37], v[4:5]
	v_pk_mul_f32 v[2:3], v[34:35], v[2:3]
	s_waitcnt lgkmcnt(2)
	v_pk_mul_f32 v[6:7], v[38:39], v[6:7]
	v_pk_mul_f32 v[8:9], v[40:41], v[8:9]
	s_waitcnt lgkmcnt(1)
	v_pk_mul_f32 v[10:11], v[42:43], v[10:11]
	v_pk_mul_f32 v[12:13], v[44:45], v[12:13]
	s_waitcnt lgkmcnt(0)
	v_pk_mul_f32 v[14:15], v[46:47], v[14:15]
	v_pk_mul_f32 v[16:17], v[48:49], v[16:17]
	v_add_u32_e32 v157, s99, v157
	v_add_u32_e32 v176, s99, v176
	v_add_u32_e32 v193, s99, v193
	v_add_u32_e32 v194, s99, v194
	v_add_u32_e32 v195, s99, v195
	v_add_u32_e32 v196, s99, v196
	v_add_u32_e32 v212, s99, v212
	s_add_i32 s22, s22, s99
	s_sub_i32 s99, 0, s99
	s_cbranch_vccnz .LBB0_992
.LBB0_984:
	v_mov_b32_e32 v250, s101
	v_mov_b32_e32 v251, s100
	ds_write_b32 v250, v251
	s_mov_b32 s4, 0
	v_mov_b32_e32 v250, 0x20800
.Lsc_wait0:
	ds_read_b32 v252, v250
	s_waitcnt lgkmcnt(0)
	v_readfirstlane_b32 s5, v252
	s_cmp_gt_u32 s5, s100
	s_cbranch_scc1 .Lsc_go0
	s_cmp_lg_u32 s98, 0
	s_cbranch_scc1 .Lsc_go0
	s_sleep 1
	s_add_i32 s4, s4, 1
	s_cmp_lt_u32 s4, 0x20000
	s_cbranch_scc1 .Lsc_wait0
	s_mov_b32 s98, 1
.Lsc_go0:
	s_add_i32 s100, s100, 1
	s_add_i32 s10, s21, 1
.LBB0_989:
	ds_read_b128 v[66:69], v194 offset:8192
	ds_read_b128 v[34:37], v194
	ds_read_b128 v[38:41], v194 offset:32
	ds_read_b128 v[82:85], v194 offset:8224
	v_cvt_pk_bf16_f32 v214, v18, v19
	v_cvt_pk_bf16_f32 v215, v20, v21
	s_waitcnt lgkmcnt(2)
	v_mfma_f32_32x32x16_bf16 v[50:65], v[66:69], v[34:37], 0
	v_cvt_pk_bf16_f32 v216, v22, v23
	v_cvt_pk_bf16_f32 v217, v24, v25
	v_cvt_pk_bf16_f32 v228, v26, v27
	v_cvt_pk_bf16_f32 v229, v28, v29
	v_cvt_pk_bf16_f32 v230, v30, v31
	v_cvt_pk_bf16_f32 v231, v32, v33
	v_add_u32_e32 v106, 0x5000, v196
	s_waitcnt lgkmcnt(0)
	v_mfma_f32_32x32x16_bf16 v[50:65], v[82:85], v[38:41], v[50:65]
	ds_read_b128 v[86:89], v194 offset:8256
	ds_read_b128 v[34:37], v194 offset:64
	ds_read_b128 v[90:93], v194 offset:8288
	ds_read_b128 v[38:41], v194 offset:96
	s_add_i32 s14, s20, 2
	s_and_b64 s[8:9], s[92:93], exec
	s_cselect_b32 s8, s21, s14
	s_lshl_b32 s8, s8, 5
	s_add_i32 s8, s8, s12
	s_add_i32 s18, s21, 2
	s_waitcnt lgkmcnt(2)
	v_mfma_f32_32x32x16_bf16 v[50:65], v[86:89], v[34:37], v[50:65]
	ds_read_b128 v[34:37], v194 offset:4096
	ds_read_b128 v[70:73], v194 offset:12288
	ds_read_b128 v[74:77], v194 offset:4128
	ds_read_b128 v[94:97], v194 offset:12320
	s_cmp_ge_u32 s18, s11
	s_waitcnt lgkmcnt(4)
	v_mfma_f32_32x32x16_bf16 v[50:65], v[90:93], v[38:41], v[50:65]
	s_waitcnt lgkmcnt(2)
	v_mfma_f32_32x32x16_bf16 v[34:49], v[34:37], v[70:73], 0
	s_nop 9
	v_cndmask_b32_e64 v0, 0, v50, s[0:1]
	v_cndmask_b32_e64 v50, 0, v51, s[2:3]
	v_cndmask_b32_e64 v51, 0, v52, s[34:35]
	v_cndmask_b32_e64 v52, 0, v53, s[36:37]
	v_cndmask_b32_e64 v53, 0, v54, s[38:39]
	v_cndmask_b32_e64 v57, 0, v57, s[44:45]
	v_cvt_pk_bf16_f32 v54, v0, v50
	s_waitcnt lgkmcnt(0)
	v_mfma_f32_32x32x16_bf16 v[34:49], v[74:77], v[94:97], v[34:49]
	ds_read_b128 v[74:77], v194 offset:4160
	ds_read_b128 v[98:101], v194 offset:12352
	ds_read_b128 v[78:81], v194 offset:4192
	ds_read_b128 v[102:105], v194 offset:12384
	v_cndmask_b32_e64 v58, 0, v58, s[46:47]
	v_cndmask_b32_e64 v59, 0, v59, s[48:49]
	v_cndmask_b32_e64 v60, 0, v60, s[50:51]
	v_cndmask_b32_e64 v61, 0, v61, s[52:53]
	v_cndmask_b32_e64 v62, 0, v62, s[54:55]
	v_cndmask_b32_e64 v63, 0, v63, s[56:57]
	s_waitcnt lgkmcnt(2)
	v_mfma_f32_32x32x16_bf16 v[34:49], v[74:77], v[98:101], v[34:49]
	v_cndmask_b32_e64 v64, 0, v64, s[58:59]
	v_cndmask_b32_e64 v0, 0, v65, s[60:61]
	v_cvt_pk_bf16_f32 v58, v58, v59
	v_cvt_pk_bf16_f32 v59, v60, v61
	v_cvt_pk_bf16_f32 v60, v62, v63
	v_cvt_pk_bf16_f32 v61, v64, v0
	s_waitcnt lgkmcnt(0)
	v_mfma_f32_32x32x16_bf16 v[34:49], v[78:81], v[102:105], v[34:49]
	v_mfma_f32_32x32x16_bf16 v[66:81], v[66:69], v[70:73], 0
	s_nop 10
	v_cndmask_b32_e64 v34, v34, 0, s[62:63]
	v_cndmask_b32_e64 v35, 0, v35, s[0:1]
	v_cvt_pk_bf16_f32 v34, v34, v35
	v_cndmask_b32_e64 v42, v42, 0, s[76:77]
	v_cndmask_b32_e64 v43, v43, 0, s[78:79]
	v_cvt_pk_bf16_f32 v42, v42, v43
	v_cndmask_b32_e64 v43, v44, 0, s[80:81]
	v_mfma_f32_32x32x16_bf16 v[66:81], v[82:85], v[94:97], v[66:81]
	v_cndmask_b32_e64 v82, 0, v55, s[40:41]
	v_cndmask_b32_e64 v83, 0, v56, s[42:43]
	v_cvt_pk_bf16_f32 v55, v51, v52
	v_cvt_pk_bf16_f32 v56, v53, v82
	v_cvt_pk_bf16_f32 v57, v83, v57
	ds_read_b64_tr_b16 v[146:147], v157 offset:0x4000
	ds_read_b64_tr_b16 v[148:149], v157 offset:0x4000+1024
	ds_read_b64_tr_b16 v[134:135], v157 offset:0x4000+2048
	ds_read_b64_tr_b16 v[136:137], v157 offset:0x4000+3072
	ds_read_b64_tr_b16 v[126:127], v176 offset:0x1000
	ds_read_b64_tr_b16 v[128:129], v176 offset:0x1000+1024
	ds_read_b64_tr_b16 v[122:123], v176 offset:0x1000+2048
	ds_read_b64_tr_b16 v[124:125], v176 offset:0x1000+3072
	ds_read_b64_tr_b16 v[118:119], v176 offset:0x1000+64
	ds_read_b64_tr_b16 v[120:121], v176 offset:0x1000+64+1024
	ds_read_b64_tr_b16 v[114:115], v176 offset:0x1000+64+2048
	ds_read_b64_tr_b16 v[116:117], v176 offset:0x1000+64+3072
	ds_read_b64_tr_b16 v[50:51], v176 offset:0x2000
	ds_read_b64_tr_b16 v[52:53], v176 offset:0x2000+1024
	ds_read_b64_tr_b16 v[138:139], v176 offset:0x2000+2048
	ds_read_b64_tr_b16 v[140:141], v176 offset:0x2000+3072
	ds_read_b64_tr_b16 v[142:143], v176 offset:0x2000+64
	ds_read_b64_tr_b16 v[144:145], v176 offset:0x2000+64+1024
	ds_read_b64_tr_b16 v[130:131], v176 offset:0x2000+64+2048
	ds_read_b64_tr_b16 v[132:133], v176 offset:0x2000+64+3072
	s_waitcnt lgkmcnt(0)
	ds_read2_b64 v[242:245], v106 offset0:4 offset1:6
	v_mfma_f32_32x32x16_bf16 v[66:81], v[86:89], v[98:101], v[66:81]
	ds_read2_b64 v[98:101], v195 offset0:8 offset1:10
	v_cndmask_b32_e64 v44, v45, 0, s[82:83]
	v_cvt_pk_bf16_f32 v43, v43, v44
	v_cndmask_b32_e64 v44, v46, 0, s[84:85]
	v_mfma_f32_32x32x16_bf16 v[66:81], v[90:93], v[102:105], v[66:81]
	ds_read2_b64 v[102:105], v195 offset0:12 offset1:14
	v_mfma_f32_32x32x16_bf16 v[82:97], v[54:57], v[146:149], 0
	ds_read2_b64 v[54:57], v195 offset1:2
	s_nop 8
	v_cndmask_b32_e64 v0, v66, 0, s[62:63]
	v_cndmask_b32_e64 v62, 0, v67, s[0:1]
	v_cndmask_b32_e64 v63, v68, 0, s[64:65]
	v_cndmask_b32_e64 v64, v69, 0, s[66:67]
	v_cndmask_b32_e64 v65, v70, 0, s[68:69]
	v_cndmask_b32_e64 v66, v71, 0, s[70:71]
	v_mfma_f32_32x32x16_bf16 v[82:97], v[58:61], v[134:137], v[82:97]
	ds_read2_b64 v[58:61], v195 offset0:4 offset1:6
	v_cndmask_b32_e64 v67, v73, 0, s[74:75]
	v_cndmask_b32_e64 v213, v75, 0, s[78:79]
	v_cndmask_b32_e64 v218, v76, 0, s[80:81]
	v_cndmask_b32_e64 v219, v77, 0, s[82:83]
	v_cvt_pk_bf16_f32 v75, v12, v13
	v_cvt_pk_bf16_f32 v76, v14, v15
	s_waitcnt lgkmcnt(1)
	v_mfma_f32_32x32x16_bf16 v[82:97], v[54:57], v[214:217], v[82:97]
	v_cndmask_b32_e64 v57, v72, 0, s[72:73]
	v_cvt_pk_bf16_f32 v54, v0, v62
	v_cvt_pk_bf16_f32 v55, v63, v64
	v_cvt_pk_bf16_f32 v56, v65, v66
	v_cvt_pk_bf16_f32 v57, v57, v67
	v_cndmask_b32_e64 v0, v74, 0, s[76:77]
	v_cvt_pk_bf16_f32 v74, v10, v11
	s_waitcnt lgkmcnt(0)
	v_mfma_f32_32x32x16_bf16 v[82:97], v[58:61], v[228:231], v[82:97]
	v_cvt_pk_bf16_f32 v77, v16, v17
	v_cndmask_b32_e64 v237, v78, 0, s[84:85]
	v_cndmask_b32_e64 v246, v79, 0, s[86:87]
	v_cvt_pk_bf16_f32 v78, v0, v213
	v_cvt_pk_bf16_f32 v79, v218, v219
	v_add_u32_e32 v0, 0x3000, v195
	v_mfma_f32_32x32x16_bf16 v[58:73], v[54:57], v[146:149], 0
	v_cvt_pk_bf16_f32 v54, v2, v3
	v_cvt_pk_bf16_f32 v55, v4, v5
	v_cvt_pk_bf16_f32 v56, v6, v7
	v_cvt_pk_bf16_f32 v57, v8, v9
	s_nop 1
	v_mfma_f32_32x32x16_bf16 v[82:97], v[98:101], v[54:57], v[82:97]
	ds_read2_b64 v[98:101], v106 offset1:2
	v_mfma_f32_32x32x16_bf16 v[82:97], v[102:105], v[74:77], v[82:97]
	s_nop 11
	v_cvt_pk_bf16_f32 v82, v82, v83
	v_cvt_pk_bf16_f32 v83, v84, v85
	v_cvt_pk_bf16_f32 v84, v86, v87
	v_cvt_pk_bf16_f32 v85, v88, v89
	s_waitcnt lgkmcnt(0)
	s_nop 0
	v_mfma_f32_32x32x16_bf16 v[98:113], v[98:101], v[82:85], 0
	v_cndmask_b32_e64 v84, v80, 0, s[88:89]
	v_cndmask_b32_e64 v85, v81, 0, s[90:91]
	v_cvt_pk_bf16_f32 v80, v90, v91
	v_cvt_pk_bf16_f32 v81, v92, v93
	v_cvt_pk_bf16_f32 v82, v94, v95
	v_cvt_pk_bf16_f32 v83, v96, v97
	ds_read2_b64 v[90:93], v0 offset0:4 offset1:6
	s_nop 0
	v_mfma_f32_32x32x16_bf16 v[98:113], v[242:245], v[80:83], v[98:113]
	v_cvt_pk_bf16_f32 v80, v237, v246
	v_cvt_pk_bf16_f32 v81, v84, v85
	ds_read2_b64 v[82:85], v0 offset1:2
	s_nop 0
	v_mfma_f32_32x32x16_bf16 v[58:73], v[78:81], v[134:137], v[58:73]
	s_nop 6
	v_cvt_pk_bf16_f32 v86, v98, v99
	v_cvt_pk_bf16_f32 v87, v100, v101
	v_cvt_pk_bf16_f32 v88, v102, v103
	v_cvt_pk_bf16_f32 v89, v104, v105
	v_cvt_pk_bf16_f32 v78, v106, v107
	v_cvt_pk_bf16_f32 v79, v108, v109
	v_cvt_pk_bf16_f32 v80, v110, v111
	s_waitcnt lgkmcnt(0)
	v_mfma_f32_32x32x16_bf16 v[58:73], v[82:85], v[214:217], v[58:73]
	ds_read2_b64 v[82:85], v0 offset0:8 offset1:10
	v_cvt_pk_bf16_f32 v81, v112, v113
	v_mfma_f32_32x32x16_bf16 v[58:73], v[90:93], v[228:231], v[58:73]
	ds_read2_b64 v[90:93], v0 offset0:12 offset1:14
	v_cndmask_b32_e64 v0, v36, 0, s[64:65]
	v_cndmask_b32_e64 v36, v37, 0, s[66:67]
	v_cndmask_b32_e64 v37, v38, 0, s[68:69]
	v_cndmask_b32_e64 v38, v39, 0, s[70:71]
	v_cndmask_b32_e64 v39, v40, 0, s[72:73]
	v_cndmask_b32_e64 v40, v41, 0, s[74:75]
	s_waitcnt lgkmcnt(1)
	v_mfma_f32_32x32x16_bf16 v[58:73], v[82:85], v[54:57], v[58:73]
	v_cvt_pk_bf16_f32 v35, v0, v36
	v_cvt_pk_bf16_f32 v36, v37, v38
	v_cvt_pk_bf16_f32 v37, v39, v40
	v_cndmask_b32_e64 v0, v47, 0, s[86:87]
	v_cvt_pk_bf16_f32 v44, v44, v0
	v_cndmask_b32_e64 v0, v48, 0, s[88:89]
	v_cndmask_b32_e64 v38, v49, 0, s[90:91]
	s_waitcnt lgkmcnt(0)
	v_mfma_f32_32x32x16_bf16 v[58:73], v[90:93], v[74:77], v[58:73]
	v_cvt_pk_bf16_f32 v45, v0, v38
	v_mfma_f32_32x32x16_bf16 v[58:73], v[34:37], v[86:89], v[58:73]
	v_mfma_f32_32x32x16_bf16 v[58:73], v[42:45], v[78:81], v[58:73]
	v_mfma_f32_32x32x16_bf16 v[18:33], v[126:129], v[86:89], v[18:33]
	s_movk_i32 s4, 0x1000
	v_mov_b32_e32 v252, s8
	v_mad_u64_u32 v[250:251], s[6:7], v252, s4, v[158:159]
	s_nop 0
	v_readfirstlane_b32 s6, v250
	v_readfirstlane_b32 s7, v251
	s_nop 10
	global_store_dword v155, v58, s[6:7]
	global_store_dword v197, v59, s[6:7]
	global_store_dword v198, v60, s[6:7]
	global_store_dword v199, v61, s[6:7]
	global_store_dword v200, v62, s[6:7]
	global_store_dword v201, v63, s[6:7]
	global_store_dword v202, v64, s[6:7]
	global_store_dword v203, v65, s[6:7]
	global_store_dword v204, v66, s[6:7]
	global_store_dword v205, v67, s[6:7]
	global_store_dword v206, v68, s[6:7]
	global_store_dword v207, v69, s[6:7]
	global_store_dword v208, v70, s[6:7]
	global_store_dword v209, v71, s[6:7]
	v_mfma_f32_32x32x16_bf16 v[34:49], v[142:145], v[146:149], 0
	global_store_dword v210, v72, s[6:7]
	v_mfma_f32_32x32x16_bf16 v[50:65], v[50:53], v[146:149], 0
	global_store_dword v211, v73, s[6:7]
	v_add_u32_e32 v144, s22, v160
	s_cselect_b64 s[8:9], -1, 0
	s_and_b64 vcc, exec, s[8:9]
	v_mfma_f32_32x32x16_bf16 v[2:17], v[118:121], v[86:89], v[2:17]
	v_mfma_f32_32x32x16_bf16 v[34:49], v[130:133], v[134:137], v[34:49]
	v_mfma_f32_32x32x16_bf16 v[18:33], v[122:125], v[78:81], v[18:33]
	ds_read_b128 v[130:133], v144 offset:22528
	ds_read_b128 v[126:129], v144 offset:22560
	ds_read_b128 v[122:125], v144 offset:22592
	ds_read_b128 v[108:111], v144 offset:22624
	ds_read_b128 v[100:103], v144 offset:22656
	ds_read_b128 v[96:99], v144 offset:22688
	ds_read_b128 v[104:107], v144 offset:22720
	ds_read_b128 v[92:95], v144 offset:22752
	v_mov_b32_e32 v250, s101
	v_mov_b32_e32 v251, s100
	ds_write_b32 v250, v251
	s_mov_b32 s4, 0
	v_mov_b32_e32 v250, 0x20800

.Lsc_go1:
	s_add_i32 s100, s100, 1
	v_mfma_f32_32x32x16_bf16 v[50:65], v[138:141], v[134:137], v[50:65]
	v_mfma_f32_32x32x16_bf16 v[2:17], v[114:117], v[78:81], v[2:17]
	s_branch .LBB0_983

.Lldr_start:
	s_cmp_lg_u32 s62, 4
	s_cbranch_scc1 .LBB0_1110
	s_setprio 3
	v_readlane_b32 s0, v253, 61
	v_readlane_b32 s8, v253, 7
	v_readlane_b32 s9, v253, 8
	v_readlane_b32 s12, v254, 57
	v_mov_b32_e32 v10, s0
	ds_read_b64 v[2:3], v10
	s_mov_b32 s21, 0
	s_lshl_b32 s8, s8, 1
	s_add_i32 s8, s8, s21
	s_lshl_b32 s9, s9, 1
	s_addk_i32 s9, 0xff00
	s_cmpk_gt_i32 s8, 0xff
	s_cselect_b32 s9, s9, 0x900
	s_mul_i32 s10, s21, 0xb800
	s_lshl_b32 s11, s21, 3
	s_add_i32 s11, s11, 0x20800
	s_add_i32 s12, s12, 1
	s_lshl_b32 s12, s12, 12
	s_mov_b32 s98, s12
	s_mov_b32 s28, 0
	v_lshlrev_b32_e32 v6, 4, v234
	v_and_b32_e32 v7, 0xf0, v6
	v_mov_b32_e32 v8, s11
	s_waitcnt lgkmcnt(0)
	v_readfirstlane_b32 s0, v2
	v_readfirstlane_b32 s1, v3
	s_add_u32 s2, s0, 0x5c400000
	s_addc_u32 s3, s1, 0
	s_add_u32 s4, s0, 0x72e00000
	s_addc_u32 s5, s1, 0
	s_add_u32 s6, s0, 0x74e00000
	s_addc_u32 s7, s1, 0
	s_cmpk_gt_i32 s8, 0x8ff
	s_cbranch_scc1 .Lldr_done
.Lldr_item:
	s_add_i32 s21, s8, 0xffffff00
	s_cmpk_lt_i32 s8, 0x100
	s_cselect_b32 s13, 64, 8
	s_cselect_b32 s21, s8, s21
	s_bfe_u32 s16, s21, 0x40001
	s_bfe_u32 s15, s21, 0x10005
	s_lshr_b32 s22, s21, 6
	s_lshl_b32 s32, s22, 6
	s_addk_i32 s32, 0x100
	s_lshl_b32 s22, s22, 3
	s_cmpk_lt_i32 s8, 0x100
	s_cselect_b32 s18, s32, s22
	v_lshrrev_b32_e32 v9, 3, v234
	v_sub_u32_e32 v10, 31, v9
	s_cmp_eq_u32 s15, 0
	s_cselect_b64 s[34:35], -1, 0
	s_mul_i32 s21, s16, 0x480
	s_lshl_b32 s22, s15, 9
	s_add_i32 s21, s21, s22
	v_cndmask_b32_e64 v9, v10, v9, s[34:35]
	v_and_b32_e32 v10, 0x70, v6
	v_mul_u32_u24_e32 v2, 0x4800, v9
	v_add3_u32 v2, v2, v10, s21
	s_mov_b32 s22, 0x24000
	s_cmp_eq_u32 s15, 0
	s_cselect_b32 s22, s22, 0xfffdc000
	s_lshl_b32 s36, s15, 9
	s_sub_u32 s36, 0x400, s36
	v_add_u32_e32 v3, s22, v2
	v_add_u32_e32 v4, s22, v3
	v_add_u32_e32 v5, s22, v4
	s_mov_b32 s14, 0
.Lldr_chunk:
	s_sub_i32 s19, s13, s14
	s_add_i32 s19, s19, -1
	s_cmp_eq_u32 s15, 0
	s_cselect_b32 s19, s14, s19
	s_add_i32 s19, s19, s18
	s_and_b32 s20, s14, 3
	s_mul_i32 s20, s20, 0x5c00
	s_add_i32 s20, s20, s10
	s_sub_u32 s21, s12, s98
	s_cmp_lt_u32 s21, 4
	s_cbranch_scc1 .Lldr_go
	s_add_i32 s22, s12, -3
	s_mov_b32 s32, 0
.Lldr_wait:
	ds_read2_b32 v[12:13], v8 offset0:1 offset1:2
	s_waitcnt lgkmcnt(0)
	v_readfirstlane_b32 s21, v12
	v_readfirstlane_b32 s40, v13
	s_min_u32 s21, s21, s40
	s_cmp_ge_u32 s21, s22
	s_cbranch_scc1 .Lldr_go
	s_cmp_lg_u32 s28, 0
	s_cbranch_scc1 .Lldr_go
	s_sleep 2
	s_add_i32 s32, s32, 1
	s_cmp_lt_u32 s32, 0x20000
	s_cbranch_scc1 .Lldr_wait
	s_mov_b32 s28, 1
.Lldr_go:
	s_mul_i32 s21, s19, 0x90000
	s_add_u32 s24, s2, s21
	s_addc_u32 s25, s3, 0
	s_lshl_b32 s21, s19, 1
	s_or_b32 s21, s21, s15
	s_lshl_b32 s21, s21, 4
	s_or_b32 s21, s21, s16
	s_mov_b32 m0, s20
	s_add_u32 s38, s24, s36
	s_addc_u32 s39, s25, 0
	s_nop 0
	global_load_lds_dwordx4 v2, s[24:25]
	s_addk_i32 m0, 0x400
	s_nop 0
	global_load_lds_dwordx4 v3, s[24:25]
	s_addk_i32 m0, 0x400
	s_nop 0
	global_load_lds_dwordx4 v4, s[24:25]
	s_addk_i32 m0, 0x400
	s_nop 0
	global_load_lds_dwordx4 v5, s[24:25]
	s_add_u32 s24, s24, 0x80
	s_addc_u32 s25, s25, 0
	s_addk_i32 m0, 0x400
	s_nop 0
	global_load_lds_dwordx4 v2, s[24:25]
	s_addk_i32 m0, 0x400
	s_nop 0
	global_load_lds_dwordx4 v3, s[24:25]
	s_addk_i32 m0, 0x400
	s_nop 0
	global_load_lds_dwordx4 v4, s[24:25]
	s_addk_i32 m0, 0x400
	s_nop 0
	global_load_lds_dwordx4 v5, s[24:25]
	s_add_u32 s24, s24, 0x80
	s_addc_u32 s25, s25, 0
	s_addk_i32 m0, 0x400
	s_nop 0
	global_load_lds_dwordx4 v2, s[24:25]
	s_addk_i32 m0, 0x400
	s_nop 0
	global_load_lds_dwordx4 v3, s[24:25]
	s_addk_i32 m0, 0x400
	s_nop 0
	global_load_lds_dwordx4 v4, s[24:25]
	s_addk_i32 m0, 0x400
	s_nop 0
	global_load_lds_dwordx4 v5, s[24:25]
	s_add_u32 s24, s24, 0x80
	s_addc_u32 s25, s25, 0
	s_addk_i32 m0, 0x400
	s_nop 0
	global_load_lds_dwordx4 v2, s[24:25]
	s_addk_i32 m0, 0x400
	s_nop 0
	global_load_lds_dwordx4 v3, s[24:25]
	s_addk_i32 m0, 0x400
	s_nop 0
	global_load_lds_dwordx4 v4, s[24:25]
	s_addk_i32 m0, 0x400
	s_nop 0
	global_load_lds_dwordx4 v5, s[24:25]
	s_addk_i32 m0, 0x400
	s_nop 0
	global_load_lds_dwordx4 v2, s[38:39]
	s_addk_i32 m0, 0x400
	s_nop 0
	global_load_lds_dwordx4 v3, s[38:39]
	s_addk_i32 m0, 0x400
	s_nop 0
	global_load_lds_dwordx4 v4, s[38:39]
	s_addk_i32 m0, 0x400
	s_nop 0
	global_load_lds_dwordx4 v5, s[38:39]
	s_lshl_b32 s22, s21, 11
	s_add_u32 s24, s4, s22
	s_addc_u32 s25, s5, 0
	s_addk_i32 m0, 0x400
	s_nop 0
	global_load_lds_dwordx4 v6, s[24:25]
	s_add_u32 s24, s24, 0x400
	s_addc_u32 s25, s25, 0
	s_addk_i32 m0, 0x400
	s_nop 0
	global_load_lds_dwordx4 v6, s[24:25]
	s_lshl_b32 s22, s21, 8
	s_add_u32 s24, s6, s22
	s_addc_u32 s25, s7, 0
	s_addk_i32 m0, 0x400
	s_nop 0
	global_load_lds_dwordx4 v7, s[24:25]
	s_cmp_eq_u32 s12, s98
	s_cbranch_scc1 .Lldr_nopub
	s_waitcnt vmcnt(23)
	v_mov_b32_e32 v9, s12
	ds_write_b32 v8, v9
.Lldr_nopub:
	s_add_i32 s12, s12, 1
	s_add_i32 s14, s14, 1
	s_cmp_lt_u32 s14, s13
	s_cbranch_scc1 .Lldr_chunk
	s_add_i32 s8, s8, s9
	s_cmpk_gt_i32 s8, 0x8ff
	s_cbranch_scc0 .Lldr_item
.Lldr_done:
	s_waitcnt vmcnt(0)
	v_mov_b32_e32 v9, s12
	ds_write_b32 v8, v9
	s_waitcnt lgkmcnt(0)
	s_setprio 0
	s_branch .LBB0_1110
